# final RMSNorm row loop: next row loaded one row ahead (register double buffer, counted vmcnt)
# speedup vs baseline: 1.0028x; 1.0028x over previous
.LBB0_926:
	v_readlane_b32 s0, v251, 1
	v_readlane_b32 s1, v251, 2
	s_mov_b64 s[4:5], s[0:1]
	s_cmp_ge_i32 s44, s4
	v_readlane_b32 s2, v251, 3
	v_readlane_b32 s3, v251, 4
	s_cselect_b64 s[0:1], -1, 0
	s_cmp_lt_i32 s44, s5
	s_cselect_b64 s[2:3], -1, 0
	s_and_b64 s[0:1], s[0:1], s[2:3]
	s_and_b64 vcc, exec, s[0:1]
	s_cbranch_vccz .LBB0_930
	v_readlane_b32 s1, v251, 0
	v_readfirstlane_b32 s0, v199
	s_ashr_i32 s0, s0, 6
	s_lshl_b32 s1, s1, 3
	s_add_i32 s4, s0, s1
	s_cmpk_gt_i32 s4, 0x3fff
	s_cbranch_scc1 .LBB0_930
	v_and_b32_e32 v0, 64, v222
	v_add_u32_e32 v2, 64, v0
	v_xor_b32_e32 v3, 1, v222
	v_cmp_lt_i32_e32 vcc, v3, v2
	v_readlane_b32 s2, v251, 7
	v_readlane_b32 s3, v251, 8
	v_cndmask_b32_e32 v3, v222, v3, vcc
	v_lshlrev_b32_e32 v6, 2, v3
	v_xor_b32_e32 v3, 2, v222
	v_cmp_lt_i32_e32 vcc, v3, v2
	s_load_dwordx4 s[8:11], s[2:3], 0xb8
	s_ashr_i32 s3, s0, 31
	v_cndmask_b32_e32 v3, v222, v3, vcc
	v_lshlrev_b32_e32 v7, 2, v3
	v_xor_b32_e32 v3, 4, v222
	v_cmp_lt_i32_e32 vcc, v3, v2
	s_ashr_i32 s5, s1, 31
	s_add_u32 s2, s0, s1
	v_cndmask_b32_e32 v3, v222, v3, vcc
	v_lshlrev_b32_e32 v8, 2, v3
	v_xor_b32_e32 v3, 8, v222
	v_cmp_lt_i32_e32 vcc, v3, v2
	s_addc_u32 s3, s3, s5
	s_lshl_b64 s[0:1], s[2:3], 12
	v_cndmask_b32_e32 v3, v222, v3, vcc
	v_lshlrev_b32_e32 v9, 2, v3
	v_xor_b32_e32 v3, 16, v222
	v_cmp_lt_i32_e32 vcc, v3, v2
	v_and_b32_e32 v12, 63, v199
	s_waitcnt lgkmcnt(0)
	s_add_u32 s0, s10, s0
	v_cndmask_b32_e32 v3, v222, v3, vcc
	v_lshlrev_b32_e32 v10, 2, v3
	v_xor_b32_e32 v3, 32, v222
	v_cmp_lt_i32_e32 vcc, v3, v2
	v_readlane_b32 s6, v251, 9
	v_lshlrev_b32_e32 v4, 4, v12
	v_mov_b32_e32 v5, 0
	v_cndmask_b32_e32 v2, v222, v3, vcc
	s_addc_u32 s1, s11, s1
	v_readlane_b32 s7, v251, 10
	v_lshlrev_b32_e32 v11, 2, v2
	v_lshl_add_u64 v[2:3], s[0:1], 0, v[4:5]
	s_mov_b64 s[0:1], 0x800
	s_ashr_i32 s7, s6, 31
	v_lshl_add_u64 v[0:1], s[8:9], 0, v[4:5]
	v_lshl_add_u64 v[2:3], v[2:3], 0, s[0:1]
	s_lshl_b64 s[0:1], s[6:7], 12
	s_lshl_b64 s[2:3], s[2:3], 11
	v_readlane_b32 s8, v251, 5
	v_readlane_b32 s9, v251, 6
	s_add_u32 s2, s8, s2
	v_lshlrev_b32_e32 v4, 3, v12
	s_addc_u32 s3, s9, s3
	v_lshl_add_u64 v[4:5], s[2:3], 0, v[4:5]
	s_mov_b64 s[2:3], 0xa600400
	v_lshl_add_u64 v[4:5], v[4:5], 0, s[2:3]
	s_lshl_b64 s[2:3], s[6:7], 11
	v_mov_b32_e32 v12, 0x358637bd
	s_mov_b32 s5, 0x800000
	global_load_dwordx4 v[52:55], v[0:1], off
	global_load_dwordx4 v[56:59], v[0:1], off offset:1024
	global_load_dwordx4 v[60:63], v[0:1], off offset:2048
	global_load_dwordx4 v[64:67], v[0:1], off offset:3072
	global_load_dwordx2 v[80:81], v[4:5], off offset:-1024
	global_load_dwordx2 v[82:83], v[4:5], off offset:-512
	global_load_dwordx2 v[84:85], v[4:5], off
	global_load_dwordx2 v[86:87], v[4:5], off offset:512
	v_lshl_add_u64 v[4:5], v[4:5], 0, s[2:3]
	s_waitcnt vmcnt(0)
	s_branch .Lfin_body
.LBB0_929:
	s_waitcnt vmcnt(4)
.Lfin_body:
	v_mov_b64_e32 v[18:19], v[80:81]
	v_mov_b64_e32 v[20:21], v[82:83]
	v_mov_b64_e32 v[22:23], v[84:85]
	v_mov_b64_e32 v[24:25], v[86:87]
	s_add_i32 s4, s4, s6
	s_cmpk_lt_i32 s4, 0x4000
	s_cbranch_scc0 .Lfin_nold
	global_load_dwordx2 v[80:81], v[4:5], off offset:-1024
	global_load_dwordx2 v[82:83], v[4:5], off offset:-512
	global_load_dwordx2 v[84:85], v[4:5], off
	global_load_dwordx2 v[86:87], v[4:5], off offset:512
	v_lshl_add_u64 v[4:5], v[4:5], 0, s[2:3]
.Lfin_nold:
	v_lshlrev_b32_e32 v26, 16, v18
	v_and_b32_e32 v27, 0xffff0000, v18
	v_lshlrev_b32_e32 v18, 16, v19
	v_and_b32_e32 v19, 0xffff0000, v19
	v_lshlrev_b32_e32 v29, 16, v21
	v_lshlrev_b32_e32 v28, 16, v20
	v_and_b32_e32 v21, 0xffff0000, v21
	v_and_b32_e32 v20, 0xffff0000, v20
	v_and_b32_e32 v31, 0xffff0000, v22
	v_lshlrev_b32_e32 v33, 16, v24
	v_and_b32_e32 v35, 0xffff0000, v24
	v_mul_f32_e32 v32, v19, v19
	v_mul_f32_e32 v34, v27, v27
	v_lshlrev_b32_e32 v30, 16, v22
	v_lshlrev_b32_e32 v22, 16, v23
	v_and_b32_e32 v23, 0xffff0000, v23
	v_pk_mul_f32 v[36:37], v[20:21], v[20:21]
	v_mov_b32_e32 v39, v33
	v_mul_f32_e32 v38, v31, v31
	v_pk_fma_f32 v[42:43], v[18:19], v[18:19], v[32:33] op_sel_hi:[1,1,0]
	v_pk_fma_f32 v[44:45], v[26:27], v[26:27], v[34:35] op_sel_hi:[1,1,0]
	v_lshlrev_b32_e32 v24, 16, v25
	v_and_b32_e32 v25, 0xffff0000, v25
	v_mul_f32_e32 v40, v23, v23
	v_pk_fma_f32 v[36:37], v[28:29], v[28:29], v[36:37]
	v_pk_fma_f32 v[46:47], v[30:31], v[30:31], v[38:39] op_sel_hi:[1,1,0]
	v_mov_b32_e32 v32, v44
	v_mov_b32_e32 v38, v42
	v_mul_f32_e32 v13, v35, v35
	v_mul_f32_e32 v48, v24, v24
	v_mul_f32_e32 v49, v25, v25
	v_pk_fma_f32 v[40:41], v[22:23], v[22:23], v[40:41] op_sel_hi:[1,1,0]
	v_pk_add_f32 v[42:43], v[44:45], v[42:43]
	v_pk_add_f32 v[36:37], v[36:37], v[36:37] op_sel:[0,1] op_sel_hi:[1,0]
	v_pk_mul_f32 v[38:39], v[32:33], v[38:39]
	v_mov_b32_e32 v47, v48
	v_mov_b32_e32 v41, v49
	v_mov_b32_e32 v37, v13
	v_mov_b32_e32 v43, v39
	v_pk_add_f32 v[40:41], v[46:47], v[40:41]
	v_pk_add_f32 v[36:37], v[42:43], v[36:37]
	v_mov_b32_e32 v34, v33
	v_pk_add_f32 v[36:37], v[36:37], v[40:41]
	s_nop 0
	v_add_f32_e32 v13, v36, v37
	ds_bpermute_b32 v32, v6, v13
	s_waitcnt lgkmcnt(0)
	v_add_f32_e32 v13, v13, v32
	ds_bpermute_b32 v32, v7, v13
	s_waitcnt lgkmcnt(0)
	v_add_f32_e32 v13, v13, v32
	ds_bpermute_b32 v32, v8, v13
	s_waitcnt lgkmcnt(0)
	v_add_f32_e32 v13, v13, v32
	ds_bpermute_b32 v32, v9, v13
	s_waitcnt lgkmcnt(0)
	v_add_f32_e32 v13, v13, v32
	ds_bpermute_b32 v32, v10, v13
	s_waitcnt lgkmcnt(0)
	v_add_f32_e32 v13, v13, v32
	ds_bpermute_b32 v32, v11, v13
	s_waitcnt lgkmcnt(0)
	v_add_f32_e32 v13, v13, v32
	v_fmamk_f32 v13, v13, 0x3a800000, v12
	v_mul_f32_e32 v32, 0x4b800000, v13
	v_cmp_gt_f32_e32 vcc, s5, v13
	s_nop 1
	v_cndmask_b32_e32 v13, v13, v32, vcc
	v_rsq_f32_e32 v13, v13
	s_nop 0
	v_mul_f32_e32 v32, 0x45800000, v13
	v_cndmask_b32_e32 v32, v13, v32, vcc
	v_pk_mul_f32 v[26:27], v[32:33], v[26:27] op_sel_hi:[0,1]
	v_pk_mul_f32 v[18:19], v[32:33], v[18:19] op_sel_hi:[0,1]
	v_pk_mul_f32 v[16:17], v[54:55], v[18:19]
	v_pk_mul_f32 v[14:15], v[52:53], v[26:27]
	global_store_dwordx4 v[2:3], v[14:17], off offset:-2048
	v_mov_b32_e32 v18, v29
	v_mov_b32_e32 v19, v21
	v_mov_b32_e32 v29, v20
	v_pk_mul_f32 v[18:19], v[32:33], v[18:19] op_sel_hi:[0,1]
	v_pk_mul_f32 v[20:21], v[32:33], v[28:29] op_sel_hi:[0,1]
	v_pk_mul_f32 v[68:69], v[56:57], v[20:21]
	v_pk_mul_f32 v[70:71], v[58:59], v[18:19]
	global_store_dwordx4 v[2:3], v[68:71], off offset:-1024
	v_pk_mul_f32 v[18:19], v[32:33], v[22:23] op_sel_hi:[0,1]
	v_pk_mul_f32 v[20:21], v[32:33], v[30:31] op_sel_hi:[0,1]
	v_pk_mul_f32 v[72:73], v[60:61], v[20:21]
	v_pk_mul_f32 v[74:75], v[62:63], v[18:19]
	global_store_dwordx4 v[2:3], v[72:75], off
	v_pk_mul_f32 v[18:19], v[32:33], v[24:25] op_sel_hi:[0,1]
	v_pk_mul_f32 v[20:21], v[32:33], v[34:35] op_sel_hi:[0,1]
	v_pk_mul_f32 v[76:77], v[64:65], v[20:21]
	v_pk_mul_f32 v[78:79], v[66:67], v[18:19]
	global_store_dwordx4 v[2:3], v[76:79], off offset:1024
	v_lshl_add_u64 v[2:3], v[2:3], 0, s[0:1]
	s_cbranch_scc1 .LBB0_929
